# v4 + relu^2 epilogue: dropped 128 NaN-canonicalising v_max per FF1 tile
# speedup vs baseline: 1.0015x; 1.0015x over previous
.LBB0_203:
	v_max_f32_e32 v122, 0, v122
	v_max_f32_e32 v126, 0, v126
	v_max_f32_e32 v123, 0, v123
	v_max_f32_e32 v127, 0, v127
	v_max_f32_e32 v124, 0, v124
	v_max_f32_e32 v128, 0, v128
	v_max_f32_e32 v125, 0, v125
	v_max_f32_e32 v129, 0, v129
	v_pk_mul_f32 v[122:123], v[122:123], v[136:137] op_sel_hi:[1,0]
	v_pk_mul_f32 v[124:125], v[124:125], v[136:137] op_sel_hi:[1,0]
	v_pk_mul_f32 v[126:127], v[126:127], v[136:137] op_sel_hi:[1,0]
	v_pk_mul_f32 v[128:129], v[128:129], v[136:137] op_sel_hi:[1,0]
	v_pk_mul_f32 v[124:125], v[124:125], v[124:125]
	v_pk_mul_f32 v[122:123], v[122:123], v[122:123]
	v_pk_mul_f32 v[128:129], v[128:129], v[128:129]
	v_pk_mul_f32 v[126:127], v[126:127], v[126:127]
.LBB0_204:
	v_and_b32_e32 v156, 0x78, v186
	s_mul_i32 s0, s95, 0x180
	v_or_b32_e32 v131, s0, v156
	v_cndmask_b32_e64 v154, v186, v131, s[52:53]
	v_cvt_pk_bf16_f32 v158, v122, v123
	v_mad_i64_i32 v[122:123], s[0:1], s54, v184, 0
	v_cvt_pk_bf16_f32 v159, v124, v125
	v_lshl_add_u64 v[124:125], v[122:123], 1, s[30:31]
	v_ashrrev_i32_e32 v155, 31, v154
	v_cvt_pk_bf16_f32 v160, v126, v127
	v_cvt_pk_bf16_f32 v161, v128, v129
	v_lshl_add_u64 v[122:123], v[154:155], 1, v[124:125]
	s_and_b64 vcc, exec, s[42:43]
	global_store_dwordx4 v[122:123], v[158:161], off
	s_cbranch_vccnz .LBB0_206
	v_max_f32_e32 v114, 0, v114
	v_max_f32_e32 v118, 0, v118
	v_max_f32_e32 v115, 0, v115
	v_max_f32_e32 v119, 0, v119
	v_max_f32_e32 v116, 0, v116
	v_max_f32_e32 v120, 0, v120
	v_max_f32_e32 v117, 0, v117
	v_max_f32_e32 v121, 0, v121
	v_pk_mul_f32 v[114:115], v[114:115], v[136:137] op_sel_hi:[1,0]
	v_pk_mul_f32 v[116:117], v[116:117], v[136:137] op_sel_hi:[1,0]
	v_pk_mul_f32 v[118:119], v[118:119], v[136:137] op_sel_hi:[1,0]
	v_pk_mul_f32 v[120:121], v[120:121], v[136:137] op_sel_hi:[1,0]
	v_pk_mul_f32 v[116:117], v[116:117], v[116:117]
	v_pk_mul_f32 v[114:115], v[114:115], v[114:115]
	v_pk_mul_f32 v[120:121], v[120:121], v[120:121]
	v_pk_mul_f32 v[118:119], v[118:119], v[118:119]
.LBB0_206:
	v_or_b32_e32 v126, 0x80, v186
	v_ashrrev_i32_e32 v122, 7, v126
	s_movk_i32 s0, 0xc0
	v_mad_u64_u32 v[122:123], s[0:1], v122, s0, v[156:157]
	v_cndmask_b32_e64 v122, v126, v122, s[52:53]
	v_ashrrev_i32_e32 v123, 31, v122
	v_cvt_pk_bf16_f32 v114, v114, v115
	v_cvt_pk_bf16_f32 v115, v116, v117
	v_cvt_pk_bf16_f32 v116, v118, v119
	v_cvt_pk_bf16_f32 v117, v120, v121
	v_lshl_add_u64 v[118:119], v[122:123], 1, v[124:125]
	s_and_b64 vcc, exec, s[42:43]
	global_store_dwordx4 v[118:119], v[114:117], off
	s_cbranch_vccnz .LBB0_208
	v_max_f32_e32 v106, 0, v106
	v_max_f32_e32 v110, 0, v110
	v_max_f32_e32 v107, 0, v107
	v_max_f32_e32 v111, 0, v111
	v_max_f32_e32 v108, 0, v108
	v_max_f32_e32 v112, 0, v112
	v_max_f32_e32 v109, 0, v109
	v_max_f32_e32 v113, 0, v113
	v_pk_mul_f32 v[106:107], v[106:107], v[130:131] op_sel_hi:[1,0]
	v_pk_mul_f32 v[108:109], v[108:109], v[130:131] op_sel_hi:[1,0]
	v_pk_mul_f32 v[110:111], v[110:111], v[130:131] op_sel_hi:[1,0]
	v_pk_mul_f32 v[112:113], v[112:113], v[130:131] op_sel_hi:[1,0]
	v_pk_mul_f32 v[108:109], v[108:109], v[108:109]
	v_pk_mul_f32 v[106:107], v[106:107], v[106:107]
	v_pk_mul_f32 v[112:113], v[112:113], v[112:113]
	v_pk_mul_f32 v[110:111], v[110:111], v[110:111]
.LBB0_208:
	s_nop 0
	v_cvt_pk_bf16_f32 v114, v106, v107
	v_mad_i64_i32 v[106:107], s[0:1], s54, v132, 0
	v_lshl_add_u64 v[106:107], v[106:107], 1, s[30:31]
	v_cvt_pk_bf16_f32 v115, v108, v109
	v_cvt_pk_bf16_f32 v116, v110, v111
	v_cvt_pk_bf16_f32 v117, v112, v113
	v_lshl_add_u64 v[108:109], v[154:155], 1, v[106:107]
	s_and_b64 vcc, exec, s[42:43]
	global_store_dwordx4 v[108:109], v[114:117], off
	s_cbranch_vccnz .LBB0_210
	v_max_f32_e32 v98, 0, v98
	v_max_f32_e32 v102, 0, v102
	v_max_f32_e32 v99, 0, v99
	v_max_f32_e32 v103, 0, v103
	v_max_f32_e32 v100, 0, v100
	v_max_f32_e32 v104, 0, v104
	v_max_f32_e32 v101, 0, v101
	v_max_f32_e32 v105, 0, v105
	v_pk_mul_f32 v[98:99], v[98:99], v[130:131] op_sel_hi:[1,0]
	v_pk_mul_f32 v[100:101], v[100:101], v[130:131] op_sel_hi:[1,0]
	v_pk_mul_f32 v[102:103], v[102:103], v[130:131] op_sel_hi:[1,0]
	v_pk_mul_f32 v[104:105], v[104:105], v[130:131] op_sel_hi:[1,0]
	v_pk_mul_f32 v[100:101], v[100:101], v[100:101]
	v_pk_mul_f32 v[98:99], v[98:99], v[98:99]
	v_pk_mul_f32 v[104:105], v[104:105], v[104:105]
	v_pk_mul_f32 v[102:103], v[102:103], v[102:103]
.LBB0_210:
	v_cvt_pk_bf16_f32 v98, v98, v99
	v_cvt_pk_bf16_f32 v99, v100, v101
	v_cvt_pk_bf16_f32 v100, v102, v103
	v_cvt_pk_bf16_f32 v101, v104, v105
	v_lshl_add_u64 v[102:103], v[122:123], 1, v[106:107]
	s_and_b64 vcc, exec, s[42:43]
	global_store_dwordx4 v[102:103], v[98:101], off
	s_cbranch_vccnz .LBB0_212
	v_max_f32_e32 v90, 0, v90
	v_max_f32_e32 v94, 0, v94
	v_max_f32_e32 v91, 0, v91
	v_max_f32_e32 v95, 0, v95
	v_max_f32_e32 v92, 0, v92
	v_max_f32_e32 v96, 0, v96
	v_max_f32_e32 v93, 0, v93
	v_max_f32_e32 v97, 0, v97
	v_pk_mul_f32 v[90:91], v[90:91], v[142:143] op_sel_hi:[1,0]
	v_pk_mul_f32 v[92:93], v[92:93], v[142:143] op_sel_hi:[1,0]
	v_pk_mul_f32 v[94:95], v[94:95], v[142:143] op_sel_hi:[1,0]
	v_pk_mul_f32 v[96:97], v[96:97], v[142:143] op_sel_hi:[1,0]
	v_pk_mul_f32 v[92:93], v[92:93], v[92:93]
	v_pk_mul_f32 v[90:91], v[90:91], v[90:91]
	v_pk_mul_f32 v[96:97], v[96:97], v[96:97]
	v_pk_mul_f32 v[94:95], v[94:95], v[94:95]
.LBB0_212:
	s_nop 0
	v_cvt_pk_bf16_f32 v98, v90, v91
	v_mad_i64_i32 v[90:91], s[0:1], s54, v134, 0
	v_lshl_add_u64 v[90:91], v[90:91], 1, s[30:31]
	v_cvt_pk_bf16_f32 v99, v92, v93
	v_cvt_pk_bf16_f32 v100, v94, v95
	v_cvt_pk_bf16_f32 v101, v96, v97
	v_lshl_add_u64 v[92:93], v[154:155], 1, v[90:91]
	s_and_b64 vcc, exec, s[42:43]
	global_store_dwordx4 v[92:93], v[98:101], off
	s_cbranch_vccnz .LBB0_214
	v_max_f32_e32 v82, 0, v82
	v_max_f32_e32 v86, 0, v86
	v_max_f32_e32 v83, 0, v83
	v_max_f32_e32 v87, 0, v87
	v_max_f32_e32 v84, 0, v84
	v_max_f32_e32 v88, 0, v88
	v_max_f32_e32 v85, 0, v85
	v_max_f32_e32 v89, 0, v89
	v_pk_mul_f32 v[82:83], v[82:83], v[142:143] op_sel_hi:[1,0]
	v_pk_mul_f32 v[84:85], v[84:85], v[142:143] op_sel_hi:[1,0]
	v_pk_mul_f32 v[86:87], v[86:87], v[142:143] op_sel_hi:[1,0]
	v_pk_mul_f32 v[88:89], v[88:89], v[142:143] op_sel_hi:[1,0]
	v_pk_mul_f32 v[84:85], v[84:85], v[84:85]
	v_pk_mul_f32 v[82:83], v[82:83], v[82:83]
	v_pk_mul_f32 v[88:89], v[88:89], v[88:89]
	v_pk_mul_f32 v[86:87], v[86:87], v[86:87]
.LBB0_214:
	v_cvt_pk_bf16_f32 v82, v82, v83
	v_cvt_pk_bf16_f32 v83, v84, v85
	v_cvt_pk_bf16_f32 v84, v86, v87
	v_cvt_pk_bf16_f32 v85, v88, v89
	v_lshl_add_u64 v[86:87], v[122:123], 1, v[90:91]
	s_and_b64 vcc, exec, s[42:43]
	global_store_dwordx4 v[86:87], v[82:85], off
	s_cbranch_vccnz .LBB0_216
	v_max_f32_e32 v74, 0, v74
	v_max_f32_e32 v78, 0, v78
	v_max_f32_e32 v75, 0, v75
	v_max_f32_e32 v79, 0, v79
	v_max_f32_e32 v76, 0, v76
	v_max_f32_e32 v80, 0, v80
	v_max_f32_e32 v77, 0, v77
	v_max_f32_e32 v81, 0, v81
	v_pk_mul_f32 v[74:75], v[74:75], v[138:139] op_sel_hi:[1,0]
	v_pk_mul_f32 v[76:77], v[76:77], v[138:139] op_sel_hi:[1,0]
	v_pk_mul_f32 v[78:79], v[78:79], v[138:139] op_sel_hi:[1,0]
	v_pk_mul_f32 v[80:81], v[80:81], v[138:139] op_sel_hi:[1,0]
	v_pk_mul_f32 v[76:77], v[76:77], v[76:77]
	v_pk_mul_f32 v[74:75], v[74:75], v[74:75]
	v_pk_mul_f32 v[80:81], v[80:81], v[80:81]
	v_pk_mul_f32 v[78:79], v[78:79], v[78:79]
.LBB0_216:
	s_nop 0
	v_cvt_pk_bf16_f32 v82, v74, v75
	v_mad_i64_i32 v[74:75], s[0:1], s54, v140, 0
	v_lshl_add_u64 v[74:75], v[74:75], 1, s[30:31]
	v_cvt_pk_bf16_f32 v83, v76, v77
	v_cvt_pk_bf16_f32 v84, v78, v79
	v_cvt_pk_bf16_f32 v85, v80, v81
	v_lshl_add_u64 v[76:77], v[154:155], 1, v[74:75]
	s_and_b64 vcc, exec, s[42:43]
	global_store_dwordx4 v[76:77], v[82:85], off
	s_cbranch_vccnz .LBB0_218
	v_max_f32_e32 v66, 0, v66
	v_max_f32_e32 v70, 0, v70
	v_max_f32_e32 v67, 0, v67
	v_max_f32_e32 v71, 0, v71
	v_max_f32_e32 v68, 0, v68
	v_max_f32_e32 v72, 0, v72
	v_max_f32_e32 v69, 0, v69
	v_max_f32_e32 v73, 0, v73
	v_pk_mul_f32 v[66:67], v[66:67], v[138:139] op_sel_hi:[1,0]
	v_pk_mul_f32 v[68:69], v[68:69], v[138:139] op_sel_hi:[1,0]
	v_pk_mul_f32 v[70:71], v[70:71], v[138:139] op_sel_hi:[1,0]
	v_pk_mul_f32 v[72:73], v[72:73], v[138:139] op_sel_hi:[1,0]
	v_pk_mul_f32 v[68:69], v[68:69], v[68:69]
	v_pk_mul_f32 v[66:67], v[66:67], v[66:67]
	v_pk_mul_f32 v[72:73], v[72:73], v[72:73]
	v_pk_mul_f32 v[70:71], v[70:71], v[70:71]
.LBB0_218:
	v_cvt_pk_bf16_f32 v66, v66, v67
	v_cvt_pk_bf16_f32 v67, v68, v69
	v_cvt_pk_bf16_f32 v68, v70, v71
	v_cvt_pk_bf16_f32 v69, v72, v73
	v_lshl_add_u64 v[70:71], v[122:123], 1, v[74:75]
	s_and_b64 vcc, exec, s[42:43]
	global_store_dwordx4 v[70:71], v[66:69], off
	s_cbranch_vccnz .LBB0_220
	v_max_f32_e32 v58, 0, v58
	v_max_f32_e32 v62, 0, v62
	v_max_f32_e32 v59, 0, v59
	v_max_f32_e32 v63, 0, v63
	v_max_f32_e32 v60, 0, v60
	v_max_f32_e32 v64, 0, v64
	v_max_f32_e32 v61, 0, v61
	v_max_f32_e32 v65, 0, v65
	v_pk_mul_f32 v[58:59], v[58:59], v[148:149] op_sel_hi:[1,0]
	v_pk_mul_f32 v[60:61], v[60:61], v[148:149] op_sel_hi:[1,0]
	v_pk_mul_f32 v[62:63], v[62:63], v[148:149] op_sel_hi:[1,0]
	v_pk_mul_f32 v[64:65], v[64:65], v[148:149] op_sel_hi:[1,0]
	v_pk_mul_f32 v[60:61], v[60:61], v[60:61]
	v_pk_mul_f32 v[58:59], v[58:59], v[58:59]
	v_pk_mul_f32 v[64:65], v[64:65], v[64:65]
	v_pk_mul_f32 v[62:63], v[62:63], v[62:63]
.LBB0_220:
	s_nop 0
	v_cvt_pk_bf16_f32 v66, v58, v59
	v_mad_i64_i32 v[58:59], s[0:1], s54, v144, 0
	v_lshl_add_u64 v[58:59], v[58:59], 1, s[30:31]
	v_cvt_pk_bf16_f32 v67, v60, v61
	v_cvt_pk_bf16_f32 v68, v62, v63
	v_cvt_pk_bf16_f32 v69, v64, v65
	v_lshl_add_u64 v[60:61], v[154:155], 1, v[58:59]
	s_and_b64 vcc, exec, s[42:43]
	global_store_dwordx4 v[60:61], v[66:69], off
	s_cbranch_vccnz .LBB0_222
	v_max_f32_e32 v50, 0, v50
	v_max_f32_e32 v54, 0, v54
	v_max_f32_e32 v51, 0, v51
	v_max_f32_e32 v55, 0, v55
	v_max_f32_e32 v52, 0, v52
	v_max_f32_e32 v56, 0, v56
	v_max_f32_e32 v53, 0, v53
	v_max_f32_e32 v57, 0, v57
	v_pk_mul_f32 v[50:51], v[50:51], v[148:149] op_sel_hi:[1,0]
	v_pk_mul_f32 v[52:53], v[52:53], v[148:149] op_sel_hi:[1,0]
	v_pk_mul_f32 v[54:55], v[54:55], v[148:149] op_sel_hi:[1,0]
	v_pk_mul_f32 v[56:57], v[56:57], v[148:149] op_sel_hi:[1,0]
	v_pk_mul_f32 v[52:53], v[52:53], v[52:53]
	v_pk_mul_f32 v[50:51], v[50:51], v[50:51]
	v_pk_mul_f32 v[56:57], v[56:57], v[56:57]
	v_pk_mul_f32 v[54:55], v[54:55], v[54:55]
.LBB0_222:
	v_cvt_pk_bf16_f32 v50, v50, v51
	v_cvt_pk_bf16_f32 v51, v52, v53
	v_cvt_pk_bf16_f32 v52, v54, v55
	v_cvt_pk_bf16_f32 v53, v56, v57
	v_lshl_add_u64 v[54:55], v[122:123], 1, v[58:59]
	s_and_b64 vcc, exec, s[42:43]
	global_store_dwordx4 v[54:55], v[50:53], off
	s_cbranch_vccnz .LBB0_224
	v_max_f32_e32 v42, 0, v42
	v_max_f32_e32 v46, 0, v46
	v_max_f32_e32 v43, 0, v43
	v_max_f32_e32 v47, 0, v47
	v_max_f32_e32 v44, 0, v44
	v_max_f32_e32 v48, 0, v48
	v_max_f32_e32 v45, 0, v45
	v_max_f32_e32 v49, 0, v49
	v_pk_mul_f32 v[42:43], v[42:43], v[146:147] op_sel_hi:[1,0]
	v_pk_mul_f32 v[44:45], v[44:45], v[146:147] op_sel_hi:[1,0]
	v_pk_mul_f32 v[46:47], v[46:47], v[146:147] op_sel_hi:[1,0]
	v_pk_mul_f32 v[48:49], v[48:49], v[146:147] op_sel_hi:[1,0]
	v_pk_mul_f32 v[44:45], v[44:45], v[44:45]
	v_pk_mul_f32 v[42:43], v[42:43], v[42:43]
	v_pk_mul_f32 v[48:49], v[48:49], v[48:49]
	v_pk_mul_f32 v[46:47], v[46:47], v[46:47]
.LBB0_224:
	v_add_u32_e32 v54, 0x90, v184
	v_cvt_pk_bf16_f32 v50, v42, v43
	v_mad_i64_i32 v[42:43], s[0:1], s54, v54, 0
	v_lshl_add_u64 v[42:43], v[42:43], 1, s[30:31]
	v_cvt_pk_bf16_f32 v51, v44, v45
	v_cvt_pk_bf16_f32 v52, v46, v47
	v_cvt_pk_bf16_f32 v53, v48, v49
	v_lshl_add_u64 v[44:45], v[154:155], 1, v[42:43]
	s_and_b64 vcc, exec, s[42:43]
	global_store_dwordx4 v[44:45], v[50:53], off
	s_cbranch_vccnz .LBB0_226
	v_max_f32_e32 v34, 0, v34
	v_max_f32_e32 v38, 0, v38
	v_max_f32_e32 v35, 0, v35
	v_max_f32_e32 v39, 0, v39
	v_max_f32_e32 v36, 0, v36
	v_max_f32_e32 v40, 0, v40
	v_max_f32_e32 v37, 0, v37
	v_max_f32_e32 v41, 0, v41
	v_pk_mul_f32 v[34:35], v[34:35], v[146:147] op_sel_hi:[1,0]
	v_pk_mul_f32 v[36:37], v[36:37], v[146:147] op_sel_hi:[1,0]
	v_pk_mul_f32 v[38:39], v[38:39], v[146:147] op_sel_hi:[1,0]
	v_pk_mul_f32 v[40:41], v[40:41], v[146:147] op_sel_hi:[1,0]
	v_pk_mul_f32 v[36:37], v[36:37], v[36:37]
	v_pk_mul_f32 v[34:35], v[34:35], v[34:35]
	v_pk_mul_f32 v[40:41], v[40:41], v[40:41]
	v_pk_mul_f32 v[38:39], v[38:39], v[38:39]
.LBB0_226:
	v_cvt_pk_bf16_f32 v34, v34, v35
	v_cvt_pk_bf16_f32 v35, v36, v37
	v_cvt_pk_bf16_f32 v36, v38, v39
	v_cvt_pk_bf16_f32 v37, v40, v41
	v_lshl_add_u64 v[38:39], v[122:123], 1, v[42:43]
	s_and_b64 vcc, exec, s[42:43]
	global_store_dwordx4 v[38:39], v[34:37], off
	s_cbranch_vccnz .LBB0_228
	v_max_f32_e32 v26, 0, v26
	v_max_f32_e32 v30, 0, v30
	v_max_f32_e32 v27, 0, v27
	v_max_f32_e32 v31, 0, v31
	v_max_f32_e32 v28, 0, v28
	v_max_f32_e32 v32, 0, v32
	v_max_f32_e32 v29, 0, v29
	v_max_f32_e32 v33, 0, v33
	v_pk_mul_f32 v[26:27], v[26:27], v[152:153] op_sel_hi:[1,0]
	v_pk_mul_f32 v[28:29], v[28:29], v[152:153] op_sel_hi:[1,0]
	v_pk_mul_f32 v[30:31], v[30:31], v[152:153] op_sel_hi:[1,0]
	v_pk_mul_f32 v[32:33], v[32:33], v[152:153] op_sel_hi:[1,0]
	v_pk_mul_f32 v[28:29], v[28:29], v[28:29]
	v_pk_mul_f32 v[26:27], v[26:27], v[26:27]
	v_pk_mul_f32 v[32:33], v[32:33], v[32:33]
	v_pk_mul_f32 v[30:31], v[30:31], v[30:31]
.LBB0_228:
	v_add_u32_e32 v38, 0xa0, v184
	v_cvt_pk_bf16_f32 v34, v26, v27
	v_mad_i64_i32 v[26:27], s[0:1], s54, v38, 0
	v_lshl_add_u64 v[26:27], v[26:27], 1, s[30:31]
	v_cvt_pk_bf16_f32 v35, v28, v29
	v_cvt_pk_bf16_f32 v36, v30, v31
	v_cvt_pk_bf16_f32 v37, v32, v33
	v_lshl_add_u64 v[28:29], v[154:155], 1, v[26:27]
	s_and_b64 vcc, exec, s[42:43]
	global_store_dwordx4 v[28:29], v[34:37], off
	s_cbranch_vccnz .LBB0_230
	v_max_f32_e32 v18, 0, v18
	v_max_f32_e32 v22, 0, v22
	v_max_f32_e32 v19, 0, v19
	v_max_f32_e32 v23, 0, v23
	v_max_f32_e32 v20, 0, v20
	v_max_f32_e32 v24, 0, v24
	v_max_f32_e32 v21, 0, v21
	v_max_f32_e32 v25, 0, v25
	v_pk_mul_f32 v[18:19], v[18:19], v[152:153] op_sel_hi:[1,0]
	v_pk_mul_f32 v[20:21], v[20:21], v[152:153] op_sel_hi:[1,0]
	v_pk_mul_f32 v[22:23], v[22:23], v[152:153] op_sel_hi:[1,0]
	v_pk_mul_f32 v[24:25], v[24:25], v[152:153] op_sel_hi:[1,0]
	v_pk_mul_f32 v[20:21], v[20:21], v[20:21]
	v_pk_mul_f32 v[18:19], v[18:19], v[18:19]
	v_pk_mul_f32 v[24:25], v[24:25], v[24:25]
	v_pk_mul_f32 v[22:23], v[22:23], v[22:23]
.LBB0_230:
	v_cvt_pk_bf16_f32 v18, v18, v19
	v_cvt_pk_bf16_f32 v19, v20, v21
	v_cvt_pk_bf16_f32 v20, v22, v23
	v_cvt_pk_bf16_f32 v21, v24, v25
	v_lshl_add_u64 v[22:23], v[122:123], 1, v[26:27]
	s_and_b64 vcc, exec, s[42:43]
	global_store_dwordx4 v[22:23], v[18:21], off
	s_cbranch_vccnz .LBB0_232
	v_max_f32_e32 v10, 0, v10
	v_max_f32_e32 v14, 0, v14
	v_max_f32_e32 v11, 0, v11
	v_max_f32_e32 v15, 0, v15
	v_max_f32_e32 v12, 0, v12
	v_max_f32_e32 v16, 0, v16
	v_max_f32_e32 v13, 0, v13
	v_max_f32_e32 v17, 0, v17
	v_pk_mul_f32 v[10:11], v[10:11], v[150:151] op_sel_hi:[1,0]
	v_pk_mul_f32 v[12:13], v[12:13], v[150:151] op_sel_hi:[1,0]
	v_pk_mul_f32 v[14:15], v[14:15], v[150:151] op_sel_hi:[1,0]
	v_pk_mul_f32 v[16:17], v[16:17], v[150:151] op_sel_hi:[1,0]
	v_pk_mul_f32 v[12:13], v[12:13], v[12:13]
	v_pk_mul_f32 v[10:11], v[10:11], v[10:11]
	v_pk_mul_f32 v[16:17], v[16:17], v[16:17]
	v_pk_mul_f32 v[14:15], v[14:15], v[14:15]
.LBB0_232:
	v_add_u32_e32 v22, 0xb0, v184
	v_cvt_pk_bf16_f32 v18, v10, v11
	v_mad_i64_i32 v[10:11], s[0:1], s54, v22, 0
	v_lshl_add_u64 v[10:11], v[10:11], 1, s[30:31]
	v_cvt_pk_bf16_f32 v19, v12, v13
	v_cvt_pk_bf16_f32 v20, v14, v15
	v_cvt_pk_bf16_f32 v21, v16, v17
	v_lshl_add_u64 v[12:13], v[154:155], 1, v[10:11]
	s_and_b64 vcc, exec, s[42:43]
	global_store_dwordx4 v[12:13], v[18:21], off
	s_cbranch_vccnz .LBB0_234
	v_max_f32_e32 v6, 0, v6
	v_max_f32_e32 v2, 0, v2
	v_max_f32_e32 v7, 0, v7
	v_max_f32_e32 v3, 0, v3
	v_max_f32_e32 v8, 0, v8
	v_max_f32_e32 v4, 0, v4
	v_max_f32_e32 v9, 0, v9
	v_max_f32_e32 v5, 0, v5
	v_pk_mul_f32 v[6:7], v[6:7], v[150:151] op_sel_hi:[1,0]
	v_pk_mul_f32 v[8:9], v[8:9], v[150:151] op_sel_hi:[1,0]
	v_pk_mul_f32 v[2:3], v[2:3], v[150:151] op_sel_hi:[1,0]
	v_pk_mul_f32 v[4:5], v[4:5], v[150:151] op_sel_hi:[1,0]
	v_pk_mul_f32 v[8:9], v[8:9], v[8:9]
	v_pk_mul_f32 v[6:7], v[6:7], v[6:7]
	v_pk_mul_f32 v[4:5], v[4:5], v[4:5]
	v_pk_mul_f32 v[2:3], v[2:3], v[2:3]
